# one static s_setprio 1 for waves 4-7 over the whole attention/SSD work-queue phase (sample attention, prompt attention, pass C), reset before the grid barrier
# baseline (speedup 1.0000x reference)
; #define LAS __attribute__((address_space(3)))
; __global__ void __launch_bounds__(NTHR, 2) fwd_megakernel(Params p) {
;     ...
;         float mq = 0.f, mk = 0.f;
;         for (int i = 0; i < 64; ++i) { mq = fmaxf(mq, fabsf(p.in[10][i])); mk = fmaxf(mk, fabsf(p.in[11][i])); }
;         const float thr = 56.0f + 17.0f * mq * mk;
;         LAS volatile int* sw = (LAS volatile int*)(lds + LDS_BYTES - 16);
;         unsigned* ctr = (unsigned*)(ws + WS_CTR) + rep4;
;         for (;;) {
.LBB0_546:
	s_add_u32 s4, s72, s2
	s_addc_u32 s5, s73, s3
	global_load_dwordx4 v[6:9], v4, s[4:5] offset:16
	global_load_dwordx4 v[10:13], v4, s[4:5]
	s_add_u32 s4, s74, s2
	s_addc_u32 s5, s75, s3
	global_load_dwordx4 v[14:17], v4, s[4:5]
	global_load_dwordx4 v[18:21], v4, s[4:5] offset:16
	s_add_u32 s2, s2, 32
	s_addc_u32 s3, s3, 0
	s_cmpk_eq_i32 s2, 0x100
	s_waitcnt vmcnt(2)
	v_max3_f32 v2, v2, |v10|, |v11|
	v_max3_f32 v2, v2, |v12|, |v13|
	s_waitcnt vmcnt(1)
	v_max3_f32 v3, v3, |v14|, |v15|
	v_max3_f32 v3, v3, |v16|, |v17|
	v_max3_f32 v2, v2, |v6|, |v7|
	s_waitcnt vmcnt(0)
	v_max3_f32 v3, v3, |v18|, |v19|
	v_max3_f32 v2, v2, |v8|, |v9|
	v_max3_f32 v3, v3, |v20|, |v21|
	s_cbranch_scc0 .LBB0_546
	s_add_u32 s64, s90, 0x12700000
	s_addc_u32 s65, s91, 0
	s_add_u32 s66, s90, 0xe500000
	s_addc_u32 s67, s91, 0
	s_add_u32 s2, s90, 0x25000000
	s_addc_u32 s3, s91, 0
	s_add_u32 s68, s90, 0x16900000
	s_addc_u32 s69, s91, 0
	s_add_u32 s72, s90, 0x36458400
	s_addc_u32 s73, s91, 0
	s_add_u32 s74, s90, 0x35c20000
	s_addc_u32 s42, s91, 0
	s_add_u32 s43, s90, 0x1ab00000
	s_addc_u32 s44, s91, 0
	s_add_u32 s80, s90, 0x12720000
	s_addc_u32 s81, s91, 0
	s_add_u32 s86, s90, 0x35e20100
	v_mul_f32_e32 v2, 0x41880000, v2
	s_addc_u32 s87, s91, 0
	s_add_i32 s45, 0, 0x23ff0
	v_mbcnt_hi_u32_b32 v216, -1, v157
	v_writelane_b32 v254, s2, 41
	v_fmaak_f32 v187, v3, v2, 0x42600000
	s_mov_b32 s35, 0
	v_mov_b32_e32 v4, 0
	s_movk_i32 s46, 0x600
	s_mov_b32 s47, 0xbfb8aa3b
	s_movk_i32 s48, 0x90
	s_add_i32 s49, 0, 0x16800
	s_add_i32 s50, 0, 0x12000
	s_add_i32 s51, 0, 0x1bc00
	v_mov_b32_e32 v218, 0x358637bd
	s_mov_b32 s52, 0xf800000
	v_mov_b32_e32 v219, 0x260
	s_mov_b32 s53, 0x5040100
	s_movk_i32 s54, 0x2100
	v_mov_b32_e32 v220, 0x2000
	s_movk_i32 s55, 0x2400
	v_mov_b32_e32 v221, s45
	v_and_b32_e32 v217, 64, v216
	v_add_u32_e32 v222, -1, v216
	v_add_u32_e32 v223, -2, v216
	v_add_u32_e32 v224, -4, v216
	v_add_u32_e32 v225, -8, v216
	v_add_u32_e32 v226, -16, v216
	v_subrev_u32_e32 v227, 32, v216
	v_mov_b32_e32 v228, 0x16300
	v_mov_b32_e32 v229, 0x11c00
	v_mov_b32_e32 v230, 0x3f80
	v_mov_b32_e32 v231, 0x5040100
	s_pack_ll_b32_b16 s56, 0, 0
	v_mov_b32_e32 v232, 0xff800000
	v_writelane_b32 v254, s3, 42
	s_cmp_lt_u32 s85, 4
	s_cbranch_scc1 .Lp4_prio_skip
	s_setprio 1
.Lp4_prio_skip:
	s_branch .LBB0_550

; #define GSYNC() do { bar_target += (unsigned)G; grid_barrier((unsigned*)(ws + WS_CTR) + 64, bar_target); } while (0)
; __device__ __forceinline__ void grid_barrier(unsigned* ctr, unsigned target) {
;     asm volatile("s_waitcnt vmcnt(0)" ::: "memory");
;     __syncthreads();
;     if (threadIdx.x == 0) {
;         __builtin_amdgcn_fence(__ATOMIC_RELEASE, "agent");
;         asm volatile("s_waitcnt vmcnt(0)" ::: "memory");
;         __hip_atomic_fetch_add(ctr, 1u, __ATOMIC_RELAXED, __HIP_MEMORY_SCOPE_AGENT);
;         while (__hip_atomic_load(ctr, __ATOMIC_RELAXED, __HIP_MEMORY_SCOPE_AGENT) < target) __builtin_amdgcn_s_sleep(8);
;         __builtin_amdgcn_fence(__ATOMIC_ACQUIRE, "agent");
; __global__ void __launch_bounds__(NTHR, 2) fwd_megakernel(Params p) {
;     ...
;     }
;     GSYNC();
.LBB0_668:
	s_setprio 0
	s_waitcnt vmcnt(0)
	s_barrier
	s_mov_b64 s[0:1], exec
	v_readlane_b32 s2, v254, 53
	v_readlane_b32 s3, v254, 54
	v_readlane_b32 s96, v254, 49
	v_readlane_b32 s8, v254, 55
	s_and_b64 s[2:3], s[0:1], s[2:3]
	v_readlane_b32 s16, v254, 47
	v_readlane_b32 s18, v254, 36
	v_readlane_b32 s97, v254, 50
	v_readlane_b32 s94, v254, 51
	v_readlane_b32 s9, v254, 56
	v_readlane_b32 s17, v254, 48
	v_readlane_b32 s95, v254, 52
	s_mov_b64 exec, s[2:3]
	s_cbranch_execz .LBB0_674
	s_mov_b64 s[2:3], exec
	buffer_wbl2 sc1
	s_waitcnt vmcnt(0)
	s_waitcnt vmcnt(0)
	v_mbcnt_lo_u32_b32 v2, s2, 0
	v_mbcnt_hi_u32_b32 v2, s3, v2
	v_cmp_eq_u32_e32 vcc, 0, v2
	s_and_saveexec_b64 s[4:5], vcc
	s_cbranch_execz .LBB0_671
	s_bcnt1_i32_b64 s2, s[2:3]
	v_mov_b32_e32 v2, 0
	v_mov_b32_e32 v3, s2
	global_atomic_add v2, v3, s[96:97]
